# sparse attention: ten late gather loads of the next key tile issued as one batch; PV transposed V fragments through 8 rotating register buffers
# speedup vs baseline: 1.0829x; 1.0032x over previous
; DI int shfl_i(int v, int src) { return __builtin_amdgcn_ds_bpermute(src << 2, v); }
; DI f32x4 mfma16(bf16x8 a, bf16x8 b, f32x4 c) { return __builtin_amdgcn_mfma_f32_16x16x32_bf16(a, b, c, 0, 0, 0); }
; DI void sparse_attn(const Params& p, u16* qabs, const float* ssq, const u16* ckv, const int* sel, char* smem) {
;     ...
;       f32x4 S[2];
; #pragma unroll
;       for (int mb = 0; mb < 2; ++mb) {
;         S[mb] = (f32x4){0.f, 0.f, 0.f, 0.f};
; #pragma unroll
;         for (int s = 0; s < 8; ++s) {
;           bf16x8 a = *(const bf16x8*)(tl + (16 * mb + h) * KS + 64 * s + 16 * g);
;           S[mb] = mfma16(a, qf[s], S[mb]);
;         }
;       }
; #pragma unroll
;       for (int mb = 0; mb < 2; ++mb)
; #pragma unroll
;         for (int i = 0; i < 4; ++i) {
;           const int kl = 16 * mb + 4 * g + i;
;           const int kp = shfl_i(selv, kl);
;           const float okf = (tile * 32 + kl < nsel) ? 1.f : 0.f;
;           const float pv = __builtin_amdgcn_exp2f(S[mb][i] + bias_lookup(s_relb, s_btab, kp - t, h)) * okf;
;           l += pv;
;           S[mb][i] = pv;
;         }
;       bf16x8 pf = mk8(pack2(S[0][0], S[0][1]), pack2(S[0][2], S[0][3]), pack2(S[1][0], S[1][1]), pack2(S[1][2], S[1][3]));
.LBB0_915:
	ds_read_b128 v[120:123], v226
	ds_read_b128 v[124:127], v226 offset:64
	ds_bpermute_b32 v212, v147, v230
	ds_read_b128 v[236:239], v226 offset:8768
	v_or_b32_e32 v213, s7, v132
	v_cmp_gt_i32_e32 vcc, s18, v213
	s_waitcnt lgkmcnt(3)
	v_mfma_f32_16x16x32_bf16 v[120:123], v[120:123], v[116:119], 0
	s_waitcnt lgkmcnt(1)
	v_subrev_u32_e32 v212, s2, v212
	v_med3_i32 v212, v212, s31, v217
	v_add_u32_e32 v212, 0x22c80, v212
	v_mfma_f32_16x16x32_bf16 v[120:123], v[124:127], v[112:115], v[120:123]
	ds_read_b128 v[124:127], v226 offset:128
	ds_read_u8 v212, v212
	s_waitcnt lgkmcnt(0)
	v_lshl_add_u32 v212, v212, 6, v148
	ds_read_b32 v212, v212
	v_mfma_f32_16x16x32_bf16 v[120:123], v[124:127], v[108:111], v[120:123]
	ds_read_b128 v[124:127], v226 offset:192
	s_waitcnt lgkmcnt(0)
	v_mfma_f32_16x16x32_bf16 v[120:123], v[124:127], v[104:107], v[120:123]
	ds_read_b128 v[124:127], v226 offset:256
	s_waitcnt lgkmcnt(0)
	v_mfma_f32_16x16x32_bf16 v[120:123], v[124:127], v[100:103], v[120:123]
	ds_read_b128 v[124:127], v226 offset:320
	s_waitcnt lgkmcnt(0)
	v_mfma_f32_16x16x32_bf16 v[120:123], v[124:127], v[32:35], v[120:123]
	ds_read_b128 v[124:127], v226 offset:384
	s_waitcnt lgkmcnt(0)
	v_mfma_f32_16x16x32_bf16 v[120:123], v[124:127], v[28:31], v[120:123]
	ds_read_b128 v[124:127], v226 offset:448
	s_waitcnt lgkmcnt(0)
	v_mfma_f32_16x16x32_bf16 v[124:127], v[124:127], v[24:27], v[120:123]
	s_nop 4
	ds_read_b128 v[120:123], v226 offset:8704
	s_nop 1
	v_add_f32_e32 v124, v124, v212
	ds_bpermute_b32 v212, v167, v230
	v_exp_f32_e32 v124, v124
	s_waitcnt lgkmcnt(1)
	v_mfma_f32_16x16x32_bf16 v[120:123], v[120:123], v[116:119], 0
	s_waitcnt lgkmcnt(0)
	v_subrev_u32_e32 v212, s2, v212
	v_med3_i32 v212, v212, s31, v217
	v_add_u32_e32 v212, 0x22c80, v212
	ds_read_u8 v212, v212
	v_mfma_f32_16x16x32_bf16 v[120:123], v[236:239], v[112:115], v[120:123]
	ds_read_b128 v[236:239], v226 offset:8832
	s_waitcnt lgkmcnt(1)
	v_lshl_add_u32 v212, v212, 6, v148
	ds_read_b32 v212, v212
	s_waitcnt lgkmcnt(1)
	v_mfma_f32_16x16x32_bf16 v[120:123], v[236:239], v[108:111], v[120:123]
	s_waitcnt lgkmcnt(0)
	v_add_f32_e32 v125, v125, v212
	v_exp_f32_e32 v125, v125
	v_or_b32_e32 v212, s7, v133
	v_cmp_gt_i32_e64 s[0:1], s20, v212
	v_cndmask_b32_e64 v212, 0, 1.0, vcc
	ds_read_b128 v[236:239], v226 offset:8896
	v_cndmask_b32_e64 v213, 0, 1.0, s[0:1]
	v_pk_mul_f32 v[124:125], v[212:213], v[124:125]
	ds_bpermute_b32 v212, v168, v230
	s_waitcnt lgkmcnt(1)
	v_mfma_f32_16x16x32_bf16 v[120:123], v[236:239], v[104:107], v[120:123]
	s_waitcnt lgkmcnt(0)
	v_subrev_u32_e32 v212, s2, v212
	v_med3_i32 v212, v212, s31, v217
	v_add_u32_e32 v212, 0x22c80, v212
	ds_read_u8 v212, v212
	ds_read_b128 v[236:239], v226 offset:8960
	s_waitcnt lgkmcnt(0)
	v_mfma_f32_16x16x32_bf16 v[120:123], v[236:239], v[100:103], v[120:123]
	v_lshl_add_u32 v212, v212, 6, v148
	ds_read_b32 v212, v212
	ds_read_b128 v[236:239], v226 offset:9024
	s_waitcnt lgkmcnt(0)
	v_mfma_f32_16x16x32_bf16 v[120:123], v[236:239], v[32:35], v[120:123]
	v_add_f32_e32 v126, v126, v212
	ds_bpermute_b32 v212, v169, v230
	v_exp_f32_e32 v126, v126
	ds_read_b128 v[236:239], v226 offset:9088
	v_or_b32_e32 v213, s7, v134
	v_cmp_gt_i32_e32 vcc, s18, v213
	s_waitcnt lgkmcnt(1)
	v_subrev_u32_e32 v212, s2, v212
	v_med3_i32 v212, v212, s31, v217
	v_add_u32_e32 v212, 0x22c80, v212
	ds_read_u8 v212, v212
	s_waitcnt lgkmcnt(1)
	v_mfma_f32_16x16x32_bf16 v[120:123], v[236:239], v[28:31], v[120:123]
	ds_read_b128 v[236:239], v226 offset:9152
	s_waitcnt lgkmcnt(1)
	v_lshl_add_u32 v212, v212, 6, v148
	ds_read_b32 v212, v212
	s_waitcnt lgkmcnt(1)
	v_mfma_f32_16x16x32_bf16 v[120:123], v[236:239], v[24:27], v[120:123]
	s_waitcnt lgkmcnt(0)
	v_add_f32_e32 v127, v127, v212
	v_exp_f32_e32 v127, v127
	v_or_b32_e32 v212, s7, v135
	v_cmp_gt_i32_e64 s[0:1], s20, v212
	v_cndmask_b32_e64 v212, 0, 1.0, vcc
	v_cvt_pk_bf16_f32 v236, v124, v125
	v_cndmask_b32_e64 v213, 0, 1.0, s[0:1]
	v_pk_mul_f32 v[126:127], v[212:213], v[126:127]
	ds_bpermute_b32 v212, v170, v230
	v_or_b32_e32 v213, s7, v136
	v_cmp_gt_i32_e32 vcc, s18, v213
	v_cvt_pk_bf16_f32 v237, v126, v127
	s_waitcnt lgkmcnt(0)
	v_subrev_u32_e32 v212, s2, v212
	v_med3_i32 v212, v212, s31, v217
	v_add_u32_e32 v212, 0x22c80, v212
	ds_read_u8 v212, v212
	s_waitcnt lgkmcnt(0)
	v_lshl_add_u32 v212, v212, 6, v148
	ds_read_b32 v212, v212
	s_waitcnt lgkmcnt(0)
	v_add_f32_e32 v120, v120, v212
	ds_bpermute_b32 v212, v171, v230
	v_exp_f32_e32 v120, v120
	s_waitcnt lgkmcnt(0)
	v_subrev_u32_e32 v212, s2, v212
	v_med3_i32 v212, v212, s31, v217
	v_add_u32_e32 v212, 0x22c80, v212
	ds_read_u8 v212, v212
	s_waitcnt lgkmcnt(0)
	v_lshl_add_u32 v212, v212, 6, v148
	ds_read_b32 v212, v212
	s_waitcnt lgkmcnt(0)
	v_add_f32_e32 v121, v121, v212
	v_exp_f32_e32 v121, v121
	v_or_b32_e32 v212, s7, v137
	v_cmp_gt_i32_e64 s[0:1], s20, v212
	v_cndmask_b32_e64 v212, 0, 1.0, vcc
	s_nop 0
	v_cndmask_b32_e64 v213, 0, 1.0, s[0:1]
	v_pk_mul_f32 v[120:121], v[212:213], v[120:121]
	ds_bpermute_b32 v212, v172, v230
	v_or_b32_e32 v213, s7, v138
	v_cmp_gt_i32_e32 vcc, s18, v213
	v_cvt_pk_bf16_f32 v238, v120, v121
	s_waitcnt lgkmcnt(0)
	v_subrev_u32_e32 v212, s2, v212
	v_med3_i32 v212, v212, s31, v217
	v_add_u32_e32 v212, 0x22c80, v212
	ds_read_u8 v212, v212
	s_waitcnt lgkmcnt(0)
	v_lshl_add_u32 v212, v212, 6, v148
	ds_read_b32 v212, v212
	s_waitcnt lgkmcnt(0)
	v_add_f32_e32 v122, v122, v212
	ds_bpermute_b32 v212, v173, v230
	v_exp_f32_e32 v122, v122
	s_waitcnt lgkmcnt(0)
	v_subrev_u32_e32 v212, s2, v212
	v_med3_i32 v212, v212, s31, v217
	v_add_u32_e32 v212, 0x22c80, v212
	ds_read_u8 v212, v212
	s_waitcnt lgkmcnt(0)
; DI f32x4 mfma16(bf16x8 a, bf16x8 b, f32x4 c) { return __builtin_amdgcn_mfma_f32_16x16x32_bf16(a, b, c, 0, 0, 0); }
; DI bf16x8 cat8(s16x4 lo, s16x4 hi) { return __builtin_shufflevector(lo, hi, 0, 1, 2, 3, 4, 5, 6, 7); }
; DI void sparse_attn(const Params& p, u16* qabs, const float* ssq, const u16* ckv, const int* sel, char* smem) {
;     ...
; #pragma unroll
;       for (int rb = 0; rb < 16; ++rb) {
;         s16x4 lo = tr_read(tl + (4 * g + q4) * KS + 32 * rb + 8 * p4);
;         s16x4 hi = tr_read(tl + (16 + 4 * g + q4) * KS + 32 * rb + 8 * p4);
;         O[rb] = mfma16(cat8(lo, hi), pf, O[rb]);
;       }
	v_lshl_add_u32 v212, v212, 6, v148
	ds_read_b32 v212, v212
	ds_read_b64_tr_b16 v[240:241], v149
	ds_read_b64_tr_b16 v[242:243], v149 offset:8704
	ds_read_b64_tr_b16 v[174:175], v149 offset:32
	ds_read_b64_tr_b16 v[176:177], v149 offset:8736
	ds_read_b64_tr_b16 v[178:179], v149 offset:64
	ds_read_b64_tr_b16 v[180:181], v149 offset:8768
	ds_read_b64_tr_b16 v[182:183], v149 offset:96
	ds_read_b64_tr_b16 v[184:185], v149 offset:8800
	ds_read_b64_tr_b16 v[186:187], v149 offset:128
	ds_read_b64_tr_b16 v[188:189], v149 offset:8832
	ds_read_b64_tr_b16 v[190:191], v149 offset:160
	ds_read_b64_tr_b16 v[192:193], v149 offset:8864
	ds_read_b64_tr_b16 v[194:195], v149 offset:192
	ds_read_b64_tr_b16 v[196:197], v149 offset:8896
	s_waitcnt lgkmcnt(14)
	v_add_f32_e32 v123, v123, v212
	v_exp_f32_e32 v123, v123
	v_or_b32_e32 v212, s7, v139
	v_cmp_gt_i32_e64 s[0:1], s20, v212
	v_cndmask_b32_e64 v212, 0, 1.0, vcc
	s_nop 0
	v_cndmask_b32_e64 v213, 0, 1.0, s[0:1]
	v_pk_mul_f32 v[122:123], v[212:213], v[122:123]
	s_nop 0
	v_cvt_pk_bf16_f32 v239, v122, v123
	ds_read_b64_tr_b16 v[198:199], v149 offset:224
	ds_read_b64_tr_b16 v[200:201], v149 offset:8928
	s_waitcnt lgkmcnt(14)
	v_mfma_f32_16x16x32_bf16 v[96:99], v[240:243], v[236:239], v[96:99]
	ds_read_b64_tr_b16 v[240:241], v149 offset:256
	ds_read_b64_tr_b16 v[242:243], v149 offset:8960
	s_waitcnt lgkmcnt(14)
	v_mfma_f32_16x16x32_bf16 v[92:95], v[174:177], v[236:239], v[92:95]
	ds_read_b64_tr_b16 v[174:175], v149 offset:288
	ds_read_b64_tr_b16 v[176:177], v149 offset:8992
	s_waitcnt lgkmcnt(14)
	v_mfma_f32_16x16x32_bf16 v[88:91], v[178:181], v[236:239], v[88:91]
	ds_read_b64_tr_b16 v[178:179], v149 offset:320
	ds_read_b64_tr_b16 v[180:181], v149 offset:9024
	s_waitcnt lgkmcnt(14)
	v_mfma_f32_16x16x32_bf16 v[84:87], v[182:185], v[236:239], v[84:87]
	ds_read_b64_tr_b16 v[182:183], v149 offset:352
	ds_read_b64_tr_b16 v[184:185], v149 offset:9056
	s_waitcnt lgkmcnt(14)
	v_mfma_f32_16x16x32_bf16 v[80:83], v[186:189], v[236:239], v[80:83]
	ds_read_b64_tr_b16 v[186:187], v149 offset:384
	ds_read_b64_tr_b16 v[188:189], v149 offset:9088
	s_waitcnt lgkmcnt(14)
	v_mfma_f32_16x16x32_bf16 v[76:79], v[190:193], v[236:239], v[76:79]
	ds_read_b64_tr_b16 v[190:191], v149 offset:416
	ds_read_b64_tr_b16 v[192:193], v149 offset:9120
	s_waitcnt lgkmcnt(14)
	v_mfma_f32_16x16x32_bf16 v[72:75], v[194:197], v[236:239], v[72:75]
	ds_read_b64_tr_b16 v[194:195], v149 offset:448
	ds_read_b64_tr_b16 v[196:197], v149 offset:9152
	s_waitcnt lgkmcnt(14)
	v_mfma_f32_16x16x32_bf16 v[68:71], v[198:201], v[236:239], v[68:71]
	ds_read_b64_tr_b16 v[198:199], v149 offset:480
	ds_read_b64_tr_b16 v[200:201], v149 offset:9184
	s_waitcnt lgkmcnt(14)
	v_mfma_f32_16x16x32_bf16 v[64:67], v[240:243], v[236:239], v[64:67]
	s_waitcnt lgkmcnt(12)
	v_mfma_f32_16x16x32_bf16 v[60:63], v[174:177], v[236:239], v[60:63]
	s_waitcnt lgkmcnt(10)
	v_mfma_f32_16x16x32_bf16 v[56:59], v[178:181], v[236:239], v[56:59]
	s_waitcnt lgkmcnt(8)
	v_mfma_f32_16x16x32_bf16 v[52:55], v[182:185], v[236:239], v[52:55]
	s_waitcnt lgkmcnt(6)
	v_mfma_f32_16x16x32_bf16 v[48:51], v[186:189], v[236:239], v[48:51]
	s_waitcnt lgkmcnt(4)
	v_mfma_f32_16x16x32_bf16 v[44:47], v[190:193], v[236:239], v[44:47]
	s_waitcnt lgkmcnt(2)
	v_mfma_f32_16x16x32_bf16 v[40:43], v[194:197], v[236:239], v[40:43]
	s_waitcnt lgkmcnt(0)
	v_mfma_f32_16x16x32_bf16 v[36:39], v[198:201], v[236:239], v[36:39]
	s_andn2_b64 vcc, exec, s[16:17]
	s_cbranch_vccnz .LBB0_912
; DI int shfl_i(int v, int src) { return __builtin_amdgcn_ds_bpermute(src << 2, v); }
; DI void sparse_attn(const Params& p, u16* qabs, const float* ssq, const u16* ckv, const int* sel, char* smem) {
;     ...
;       if (tile + 1 < ntile) {
;         asm volatile("s_waitcnt lgkmcnt(0)" ::: "memory");
; #pragma unroll
;         for (int it = 0; it < 6; ++it) *(u32x4*)(tl + (2 * it + (lane >> 5)) * KS + (lane & 31) * 16) = G[it];
;         __builtin_amdgcn_sched_barrier(0);
; #pragma unroll
;         for (int hf = 0; hf < 2; ++hf) {
;           u32x4 G2[5];
; #pragma unroll
;           for (int it = 0; it < 5; ++it) {
;             const int kl = 12 + 10 * hf + 2 * it + (lane >> 5);
;             const int idx = shfl_i(selv_n, kl);
;             G2[it] = *(const u32x4*)(ckv + ((size_t)b * T + idx) * 256 + (lane & 31) * 8);
;           }
; #pragma unroll
;           for (int it = 0; it < 5; ++it) *(u32x4*)(tl + (12 + 10 * hf + 2 * it + (lane >> 5)) * KS + (lane & 31) * 16) = G2[it];
;           __builtin_amdgcn_sched_barrier(0);
;         }
;         selv = selv_n;
	s_waitcnt lgkmcnt(0)
	s_waitcnt vmcnt(5)
	ds_write_b128 v228, v[0:3]
	s_waitcnt vmcnt(4)
	ds_write_b128 v228, v[4:7] offset:1088
	s_waitcnt vmcnt(3)
	ds_write_b128 v228, v[8:11] offset:2176
	s_waitcnt vmcnt(2)
	ds_write_b128 v228, v[12:15] offset:3264
	s_waitcnt vmcnt(1)
	ds_write_b128 v228, v[16:19] offset:4352
	s_waitcnt vmcnt(0)
	ds_write_b128 v228, v[20:23] offset:5440
	ds_bpermute_b32 v236, v205, v234
	ds_bpermute_b32 v240, v206, v234
	ds_bpermute_b32 v244, v207, v234
	ds_bpermute_b32 v248, v208, v234
	ds_bpermute_b32 v0, v209, v234
	ds_bpermute_b32 v4, v221, v234
	ds_bpermute_b32 v8, v222, v234
	ds_bpermute_b32 v12, v223, v234
	ds_bpermute_b32 v16, v224, v234
	ds_bpermute_b32 v20, v225, v234
	s_waitcnt lgkmcnt(9)
	v_ashrrev_i32_e32 v237, 31, v236
	v_lshl_add_u64 v[236:237], s[14:15], 0, v[236:237]
	v_lshlrev_b64 v[236:237], 9, v[236:237]
	v_lshl_add_u64 v[236:237], v[130:131], 0, v[236:237]
	global_load_dwordx4 v[236:239], v[236:237], off
	s_nop 0
	s_waitcnt lgkmcnt(8)
	v_ashrrev_i32_e32 v241, 31, v240
	v_lshl_add_u64 v[240:241], s[14:15], 0, v[240:241]
	v_lshlrev_b64 v[240:241], 9, v[240:241]
	v_lshl_add_u64 v[240:241], v[130:131], 0, v[240:241]
	global_load_dwordx4 v[240:243], v[240:241], off
	s_nop 0
	s_waitcnt lgkmcnt(7)
	v_ashrrev_i32_e32 v245, 31, v244
	v_lshl_add_u64 v[244:245], s[14:15], 0, v[244:245]
	v_lshlrev_b64 v[244:245], 9, v[244:245]
	v_lshl_add_u64 v[244:245], v[130:131], 0, v[244:245]
	global_load_dwordx4 v[244:247], v[244:245], off
	s_nop 0
	s_waitcnt lgkmcnt(6)
	v_ashrrev_i32_e32 v249, 31, v248
	v_lshl_add_u64 v[248:249], s[14:15], 0, v[248:249]
	v_lshlrev_b64 v[248:249], 9, v[248:249]
	v_lshl_add_u64 v[248:249], v[130:131], 0, v[248:249]
	global_load_dwordx4 v[248:251], v[248:249], off
	s_nop 0
	s_waitcnt lgkmcnt(5)
	v_ashrrev_i32_e32 v1, 31, v0
	v_lshl_add_u64 v[0:1], s[14:15], 0, v[0:1]
	v_lshlrev_b64 v[0:1], 9, v[0:1]
	v_lshl_add_u64 v[0:1], v[130:131], 0, v[0:1]
	global_load_dwordx4 v[0:3], v[0:1], off
	s_nop 0
	s_waitcnt lgkmcnt(4)
	v_ashrrev_i32_e32 v5, 31, v4
	v_lshl_add_u64 v[4:5], s[14:15], 0, v[4:5]
	v_lshlrev_b64 v[4:5], 9, v[4:5]
	v_lshl_add_u64 v[4:5], v[130:131], 0, v[4:5]
	global_load_dwordx4 v[4:7], v[4:5], off
	s_nop 0
	s_waitcnt lgkmcnt(3)
	v_ashrrev_i32_e32 v9, 31, v8
	v_lshl_add_u64 v[8:9], s[14:15], 0, v[8:9]
	v_lshlrev_b64 v[8:9], 9, v[8:9]
	v_lshl_add_u64 v[8:9], v[130:131], 0, v[8:9]
	global_load_dwordx4 v[8:11], v[8:9], off
	s_nop 0
	s_waitcnt lgkmcnt(2)
	v_ashrrev_i32_e32 v13, 31, v12
	v_lshl_add_u64 v[12:13], s[14:15], 0, v[12:13]
	v_lshlrev_b64 v[12:13], 9, v[12:13]
	v_lshl_add_u64 v[12:13], v[130:131], 0, v[12:13]
	global_load_dwordx4 v[12:15], v[12:13], off
	s_nop 0
	s_waitcnt lgkmcnt(1)
	v_ashrrev_i32_e32 v17, 31, v16
	v_lshl_add_u64 v[16:17], s[14:15], 0, v[16:17]
	v_lshlrev_b64 v[16:17], 9, v[16:17]
	v_lshl_add_u64 v[16:17], v[130:131], 0, v[16:17]
	global_load_dwordx4 v[16:19], v[16:17], off
	s_nop 0
	s_waitcnt lgkmcnt(0)
	v_ashrrev_i32_e32 v21, 31, v20
	v_lshl_add_u64 v[20:21], s[14:15], 0, v[20:21]
	v_lshlrev_b64 v[20:21], 9, v[20:21]
	v_lshl_add_u64 v[20:21], v[130:131], 0, v[20:21]
	global_load_dwordx4 v[20:23], v[20:21], off
	s_nop 0
	s_waitcnt vmcnt(9)
	ds_write_b128 v227, v[236:239]
	s_waitcnt vmcnt(8)
	ds_write_b128 v228, v[240:243] offset:7616
	s_waitcnt vmcnt(7)
	ds_write_b128 v228, v[244:247] offset:8704
	s_waitcnt vmcnt(6)
	ds_write_b128 v228, v[248:251] offset:9792
	s_waitcnt vmcnt(5)
	ds_write_b128 v228, v[0:3] offset:10880
	s_waitcnt vmcnt(4)
	ds_write_b128 v227, v[4:7] offset:5440
	s_waitcnt vmcnt(3)
	ds_write_b128 v228, v[8:11] offset:13056
	s_waitcnt vmcnt(2)
	ds_write_b128 v228, v[12:15] offset:14144
	s_waitcnt vmcnt(1)
	ds_write_b128 v228, v[16:19] offset:15232
	s_waitcnt vmcnt(0)
	ds_write_b128 v228, v[20:23] offset:16320
	v_mov_b32_e32 v230, v234
	s_branch .LBB0_912
